# EpiGate epilogues (attn-proj, lru-proj): all gate-operand loads of a half issued before the first counted wait (was a full wait after the first few loads)
# speedup vs baseline: 1.0078x; 1.0053x over previous
; __device__ __forceinline__ float bflo(unsigned w) { return __uint_as_float(w << 16); }
; __device__ __forceinline__ float bfhi(unsigned w) { return __uint_as_float(w & 0xffff0000u); }
; __device__ __forceinline__ u32x4 pack8(f32x4 a, f32x4 b) { u32x4 w; w.x = cvtpk(a[0], a[1]); w.y = cvtpk(a[2], a[3]); w.z = cvtpk(b[0], b[1]); w.w = cvtpk(b[2], b[3]); return w; }
;     __device__ __forceinline__ void operator()(const pg8::f32x4 (&acc)[2][2][4][2], const pg8::Unit& u, int wr, int wc, int fr, int fq) const {
;     ...
;             u32x4 sv[4][2], av[4][2];
;             const size_t off0 = (size_t)(u.pm * 256 + ai * 128 + wr * 64 + fr) * 1024 + u.pn * 256 + wc * 32 + 8 * fq;
; #pragma unroll
;             for (int m = 0; m < 4; ++m)
; #pragma unroll
;                 for (int bj = 0; bj < 2; ++bj) { sv[m][bj] = *(const u32x4*)(S + off0 + (size_t)m * 16 * 1024 + bj * 128); if (ADD) av[m][bj] = *(const u32x4*)(A + off0 + (size_t)m * 16 * 1024 + bj * 128); }
; #pragma unroll
;             for (int m = 0; m < 4; ++m)
; #pragma unroll
;                 for (int bj = 0; bj < 2; ++bj) {
;                     const u32x4 s = sv[m][bj];
;                     f32x4 v0 = acc[ai][bj][m][0], v1 = acc[ai][bj][m][1];
;                     v0[0] *= bflo(s.x); v0[1] *= bfhi(s.x); v0[2] *= bflo(s.y); v0[3] *= bfhi(s.y); v1[0] *= bflo(s.z); v1[1] *= bfhi(s.z); v1[2] *= bflo(s.w); v1[3] *= bfhi(s.w);
;                     if (ADD) { const u32x4 a = av[m][bj];
;                         v0[0] += bflo(a.x); v0[1] += bfhi(a.x); v0[2] += bflo(a.y); v0[3] += bfhi(a.y); v1[0] += bflo(a.z); v1[1] += bfhi(a.z); v1[2] += bflo(a.w); v1[3] += bfhi(a.w); }
;                     *(u32x4*)(S + off0 + (size_t)m * 16 * 1024 + bj * 128) = pack8(v0, v1);
;                 }
.LBB0_1308:
	s_lshl_b32 s0, s46, 8
	v_mov_b32_e32 v130, v170
	v_mov_b32_e32 v131, v171
	s_add_i32 s0, s0, s47
	s_nop 0
	v_add_u32_e32 v160, s0, v130
	s_lshl_b32 s0, s60, 8
	s_ashr_i32 s1, s0, 31
	s_lshl_b64 s[0:1], s[0:1], 1
	v_lshlrev_b32_e32 v130, 3, v131
	s_add_u32 s0, s56, s0
	v_ashrrev_i32_e32 v131, 31, v130
	v_ashrrev_i32_e32 v161, 31, v160
	s_addc_u32 s1, s57, s1
	v_lshl_add_u64 v[162:163], v[130:131], 1, s[0:1]
	v_lshlrev_b64 v[130:131], 11, v[160:161]
	v_lshl_add_u64 v[186:187], v[162:163], 0, v[130:131]
	global_load_dwordx4 v[174:177], v[186:187], off
	global_load_dwordx4 v[178:181], v[186:187], off offset:256
	v_add_co_u32_e32 v168, vcc, s11, v186
	s_mov_b64 s[0:1], -1
	s_nop 0
	v_addc_co_u32_e32 v169, vcc, 0, v187, vcc
	global_load_dwordx4 v[182:185], v[168:169], off
	global_load_dwordx4 v[146:149], v[168:169], off offset:256
	v_add_co_u32_e32 v166, vcc, s33, v186
	s_nop 0
	v_addc_co_u32_e32 v167, vcc, 0, v187, vcc
	global_load_dwordx4 v[142:145], v[166:167], off
	global_load_dwordx4 v[138:141], v[166:167], off offset:256
	v_add_co_u32_e32 v164, vcc, s10, v186
	s_nop 0
	v_addc_co_u32_e32 v165, vcc, 0, v187, vcc
	global_load_dwordx4 v[134:137], v[164:165], off
	global_load_dwordx4 v[130:133], v[164:165], off offset:256
	s_waitcnt vmcnt(4)
	v_lshlrev_b32_e32 v188, 16, v174
	v_and_b32_e32 v189, 0xffff0000, v174
	v_lshlrev_b32_e32 v174, 16, v175
	v_and_b32_e32 v175, 0xffff0000, v175
	v_pk_mul_f32 v[128:129], v[128:129], v[174:175]
	v_lshlrev_b32_e32 v174, 16, v176
	v_and_b32_e32 v175, 0xffff0000, v176
	v_pk_mul_f32 v[174:175], v[122:123], v[174:175]
	v_lshlrev_b32_e32 v122, 16, v177
	v_and_b32_e32 v123, 0xffff0000, v177
	v_pk_mul_f32 v[126:127], v[126:127], v[188:189]
	v_pk_mul_f32 v[176:177], v[124:125], v[122:123]
	v_cvt_pk_bf16_f32 v122, v126, v127
	v_cvt_pk_bf16_f32 v123, v128, v129
	v_cvt_pk_bf16_f32 v124, v174, v175
	v_cvt_pk_bf16_f32 v125, v176, v177
	global_store_dwordx4 v[186:187], v[122:125], off
	s_nop 1
	v_lshlrev_b32_e32 v122, 16, v178
	v_and_b32_e32 v123, 0xffff0000, v178
	v_pk_mul_f32 v[118:119], v[118:119], v[122:123]
	v_lshlrev_b32_e32 v122, 16, v179
	v_and_b32_e32 v123, 0xffff0000, v179
	v_pk_mul_f32 v[120:121], v[120:121], v[122:123]
	v_lshlrev_b32_e32 v122, 16, v180
	v_and_b32_e32 v123, 0xffff0000, v180
	v_pk_mul_f32 v[122:123], v[114:115], v[122:123]
	v_lshlrev_b32_e32 v114, 16, v181
	v_and_b32_e32 v115, 0xffff0000, v181
	v_pk_mul_f32 v[124:125], v[116:117], v[114:115]
	v_cvt_pk_bf16_f32 v114, v118, v119
	v_cvt_pk_bf16_f32 v115, v120, v121
	v_cvt_pk_bf16_f32 v116, v122, v123
	v_cvt_pk_bf16_f32 v117, v124, v125
	global_store_dwordx4 v[186:187], v[114:117], off offset:256
	s_nop 1
	v_lshlrev_b32_e32 v114, 16, v182
	v_and_b32_e32 v115, 0xffff0000, v182
	v_pk_mul_f32 v[110:111], v[110:111], v[114:115]
	v_lshlrev_b32_e32 v114, 16, v183
	v_and_b32_e32 v115, 0xffff0000, v183
	v_pk_mul_f32 v[112:113], v[112:113], v[114:115]
	v_lshlrev_b32_e32 v114, 16, v184
	v_and_b32_e32 v115, 0xffff0000, v184
	v_pk_mul_f32 v[114:115], v[106:107], v[114:115]
	v_lshlrev_b32_e32 v106, 16, v185
	v_and_b32_e32 v107, 0xffff0000, v185
	v_pk_mul_f32 v[116:117], v[108:109], v[106:107]
	v_cvt_pk_bf16_f32 v106, v110, v111
	v_cvt_pk_bf16_f32 v107, v112, v113
	v_cvt_pk_bf16_f32 v108, v114, v115
	v_cvt_pk_bf16_f32 v109, v116, v117
	global_store_dwordx4 v[168:169], v[106:109], off
	s_nop 1
	v_lshlrev_b32_e32 v106, 16, v146
	v_and_b32_e32 v107, 0xffff0000, v146
	v_pk_mul_f32 v[102:103], v[102:103], v[106:107]
	v_lshlrev_b32_e32 v106, 16, v147
	v_and_b32_e32 v107, 0xffff0000, v147
	v_pk_mul_f32 v[104:105], v[104:105], v[106:107]
	v_lshlrev_b32_e32 v106, 16, v148
	v_and_b32_e32 v107, 0xffff0000, v148
	v_pk_mul_f32 v[106:107], v[94:95], v[106:107]
	v_lshlrev_b32_e32 v94, 16, v149
	v_and_b32_e32 v95, 0xffff0000, v149
	v_pk_mul_f32 v[108:109], v[96:97], v[94:95]
	v_cvt_pk_bf16_f32 v94, v102, v103
	v_cvt_pk_bf16_f32 v95, v104, v105
	v_cvt_pk_bf16_f32 v96, v106, v107
	v_cvt_pk_bf16_f32 v97, v108, v109
	global_store_dwordx4 v[168:169], v[94:97], off offset:256
	s_waitcnt vmcnt(7)
	s_nop 0
	v_lshlrev_b32_e32 v94, 16, v142
	v_and_b32_e32 v95, 0xffff0000, v142
	v_pk_mul_f32 v[94:95], v[98:99], v[94:95]
	v_lshlrev_b32_e32 v98, 16, v144
	v_and_b32_e32 v99, 0xffff0000, v144
	v_lshlrev_b32_e32 v96, 16, v143
	v_and_b32_e32 v97, 0xffff0000, v143
	v_pk_mul_f32 v[98:99], v[90:91], v[98:99]
	v_lshlrev_b32_e32 v90, 16, v145
	v_and_b32_e32 v91, 0xffff0000, v145
	v_pk_mul_f32 v[96:97], v[100:101], v[96:97]
	v_pk_mul_f32 v[100:101], v[92:93], v[90:91]
	v_cvt_pk_bf16_f32 v90, v94, v95
	v_cvt_pk_bf16_f32 v91, v96, v97
	v_cvt_pk_bf16_f32 v92, v98, v99
	v_cvt_pk_bf16_f32 v93, v100, v101
	global_store_dwordx4 v[166:167], v[90:93], off
	s_waitcnt vmcnt(7)
	s_nop 0
	v_lshlrev_b32_e32 v90, 16, v138
	v_and_b32_e32 v91, 0xffff0000, v138
	v_pk_mul_f32 v[86:87], v[86:87], v[90:91]
	v_lshlrev_b32_e32 v90, 16, v139
	v_and_b32_e32 v91, 0xffff0000, v139
	v_pk_mul_f32 v[88:89], v[88:89], v[90:91]
	v_lshlrev_b32_e32 v90, 16, v140
	v_and_b32_e32 v91, 0xffff0000, v140
	v_pk_mul_f32 v[90:91], v[76:77], v[90:91]
	v_lshlrev_b32_e32 v76, 16, v141
	v_and_b32_e32 v77, 0xffff0000, v141
	v_pk_mul_f32 v[92:93], v[78:79], v[76:77]
	v_cvt_pk_bf16_f32 v76, v86, v87
	v_cvt_pk_bf16_f32 v77, v88, v89
	v_cvt_pk_bf16_f32 v78, v90, v91
	v_cvt_pk_bf16_f32 v79, v92, v93
	global_store_dwordx4 v[166:167], v[76:79], off offset:256
	s_waitcnt vmcnt(7)
; __device__ __forceinline__ float bflo(unsigned w) { return __uint_as_float(w << 16); }
; __device__ __forceinline__ float bfhi(unsigned w) { return __uint_as_float(w & 0xffff0000u); }
; __device__ __forceinline__ u32x4 pack8(f32x4 a, f32x4 b) { u32x4 w; w.x = cvtpk(a[0], a[1]); w.y = cvtpk(a[2], a[3]); w.z = cvtpk(b[0], b[1]); w.w = cvtpk(b[2], b[3]); return w; }
;     __device__ __forceinline__ void operator()(const pg8::f32x4 (&acc)[2][2][4][2], const pg8::Unit& u, int wr, int wc, int fr, int fq) const {
;     ...
;             u32x4 sv[4][2], av[4][2];
;             const size_t off0 = (size_t)(u.pm * 256 + ai * 128 + wr * 64 + fr) * 1024 + u.pn * 256 + wc * 32 + 8 * fq;
; #pragma unroll
;             for (int m = 0; m < 4; ++m)
; #pragma unroll
;                 for (int bj = 0; bj < 2; ++bj) { sv[m][bj] = *(const u32x4*)(S + off0 + (size_t)m * 16 * 1024 + bj * 128); if (ADD) av[m][bj] = *(const u32x4*)(A + off0 + (size_t)m * 16 * 1024 + bj * 128); }
; #pragma unroll
;             for (int m = 0; m < 4; ++m)
; #pragma unroll
;                 for (int bj = 0; bj < 2; ++bj) {
;                     const u32x4 s = sv[m][bj];
;                     f32x4 v0 = acc[ai][bj][m][0], v1 = acc[ai][bj][m][1];
;                     v0[0] *= bflo(s.x); v0[1] *= bfhi(s.x); v0[2] *= bflo(s.y); v0[3] *= bfhi(s.y); v1[0] *= bflo(s.z); v1[1] *= bfhi(s.z); v1[2] *= bflo(s.w); v1[3] *= bfhi(s.w);
;                     if (ADD) { const u32x4 a = av[m][bj];
;                         v0[0] += bflo(a.x); v0[1] += bfhi(a.x); v0[2] += bflo(a.y); v0[3] += bfhi(a.y); v1[0] += bflo(a.z); v1[1] += bfhi(a.z); v1[2] += bflo(a.w); v1[3] += bfhi(a.w); }
;                     *(u32x4*)(S + off0 + (size_t)m * 16 * 1024 + bj * 128) = pack8(v0, v1);
;                 }
	s_nop 0
	v_lshlrev_b32_e32 v76, 16, v134
	v_and_b32_e32 v77, 0xffff0000, v134
	v_pk_mul_f32 v[76:77], v[82:83], v[76:77]
	v_lshlrev_b32_e32 v82, 16, v136
	v_and_b32_e32 v83, 0xffff0000, v136
	v_lshlrev_b32_e32 v78, 16, v135
	v_and_b32_e32 v79, 0xffff0000, v135
	v_pk_mul_f32 v[82:83], v[72:73], v[82:83]
	v_lshlrev_b32_e32 v72, 16, v137
	v_and_b32_e32 v73, 0xffff0000, v137
	v_pk_mul_f32 v[78:79], v[84:85], v[78:79]
	v_pk_mul_f32 v[84:85], v[74:75], v[72:73]
	v_cvt_pk_bf16_f32 v72, v76, v77
	v_cvt_pk_bf16_f32 v73, v78, v79
	v_cvt_pk_bf16_f32 v74, v82, v83
	v_cvt_pk_bf16_f32 v75, v84, v85
	global_store_dwordx4 v[164:165], v[72:75], off
	s_waitcnt vmcnt(7)
	s_nop 0
	v_lshlrev_b32_e32 v72, 16, v130
	v_and_b32_e32 v73, 0xffff0000, v130
	v_pk_mul_f32 v[68:69], v[68:69], v[72:73]
	v_lshlrev_b32_e32 v72, 16, v131
	v_and_b32_e32 v73, 0xffff0000, v131
	v_pk_mul_f32 v[70:71], v[70:71], v[72:73]
	v_lshlrev_b32_e32 v72, 16, v132
	v_and_b32_e32 v73, 0xffff0000, v132
	v_pk_mul_f32 v[72:73], v[64:65], v[72:73]
	v_lshlrev_b32_e32 v64, 16, v133
	v_and_b32_e32 v65, 0xffff0000, v133
	v_pk_mul_f32 v[74:75], v[66:67], v[64:65]
	v_cvt_pk_bf16_f32 v64, v68, v69
	v_cvt_pk_bf16_f32 v65, v70, v71
	v_cvt_pk_bf16_f32 v66, v72, v73
	v_cvt_pk_bf16_f32 v67, v74, v75
	global_store_dwordx4 v[164:165], v[64:67], off offset:256
	s_nop 1
	v_add_u32_e32 v64, 0x80, v160
	v_ashrrev_i32_e32 v65, 31, v64
	v_lshlrev_b64 v[64:65], 11, v[64:65]
	v_lshl_add_u64 v[78:79], v[162:163], 0, v[64:65]
	global_load_dwordx4 v[66:69], v[78:79], off
	global_load_dwordx4 v[70:73], v[78:79], off offset:256
	v_add_co_u32_e32 v102, vcc, s11, v78
	s_nop 0
	v_addc_co_u32_e32 v103, vcc, 0, v79, vcc
	global_load_dwordx4 v[74:77], v[102:103], off
	global_load_dwordx4 v[82:85], v[102:103], off offset:256
	v_add_co_u32_e32 v104, vcc, s33, v78
	s_nop 0
	v_addc_co_u32_e32 v105, vcc, 0, v79, vcc
	global_load_dwordx4 v[86:89], v[104:105], off
	global_load_dwordx4 v[90:93], v[104:105], off offset:256
	v_add_co_u32_e32 v64, vcc, s10, v78
	s_nop 0
	v_addc_co_u32_e32 v65, vcc, 0, v79, vcc
	global_load_dwordx4 v[94:97], v[64:65], off
	global_load_dwordx4 v[98:101], v[64:65], off offset:256
	s_waitcnt vmcnt(7)
	v_lshlrev_b32_e32 v106, 16, v66
	v_and_b32_e32 v107, 0xffff0000, v66
	v_lshlrev_b32_e32 v66, 16, v67
	v_and_b32_e32 v67, 0xffff0000, v67
	v_pk_mul_f32 v[62:63], v[62:63], v[66:67]
	v_lshlrev_b32_e32 v66, 16, v68
	v_and_b32_e32 v67, 0xffff0000, v68
	v_pk_mul_f32 v[66:67], v[56:57], v[66:67]
	v_lshlrev_b32_e32 v56, 16, v69
	v_and_b32_e32 v57, 0xffff0000, v69
	v_pk_mul_f32 v[60:61], v[60:61], v[106:107]
	v_pk_mul_f32 v[68:69], v[58:59], v[56:57]
	v_cvt_pk_bf16_f32 v56, v60, v61
	v_cvt_pk_bf16_f32 v57, v62, v63
	v_cvt_pk_bf16_f32 v58, v66, v67
	v_cvt_pk_bf16_f32 v59, v68, v69
	global_store_dwordx4 v[78:79], v[56:59], off
	s_andn2_b64 vcc, exec, s[36:37]
	s_waitcnt vmcnt(7)
	v_lshlrev_b32_e32 v56, 16, v70
	v_and_b32_e32 v57, 0xffff0000, v70
	v_pk_mul_f32 v[52:53], v[52:53], v[56:57]
	v_lshlrev_b32_e32 v56, 16, v71
	v_and_b32_e32 v57, 0xffff0000, v71
	v_pk_mul_f32 v[54:55], v[54:55], v[56:57]
	v_lshlrev_b32_e32 v56, 16, v72
	v_and_b32_e32 v57, 0xffff0000, v72
	v_pk_mul_f32 v[56:57], v[44:45], v[56:57]
	v_lshlrev_b32_e32 v44, 16, v73
	v_and_b32_e32 v45, 0xffff0000, v73
	v_pk_mul_f32 v[58:59], v[46:47], v[44:45]
	v_cvt_pk_bf16_f32 v44, v52, v53
	v_cvt_pk_bf16_f32 v45, v54, v55
	v_cvt_pk_bf16_f32 v46, v56, v57
	v_cvt_pk_bf16_f32 v47, v58, v59
	global_store_dwordx4 v[78:79], v[44:47], off offset:256
	s_waitcnt vmcnt(7)
; #define PG8_BAR __builtin_amdgcn_s_barrier()
; __device__ __forceinline__ float bflo(unsigned w) { return __uint_as_float(w << 16); }
; __device__ __forceinline__ float bfhi(unsigned w) { return __uint_as_float(w & 0xffff0000u); }
; __device__ __forceinline__ u32x4 pack8(f32x4 a, f32x4 b) { u32x4 w; w.x = cvtpk(a[0], a[1]); w.y = cvtpk(a[2], a[3]); w.z = cvtpk(b[0], b[1]); w.w = cvtpk(b[2], b[3]); return w; }
; template <class Epi, class Sched, bool ALIGN_EPI = false, bool SP2 = false>
; __device__ __forceinline__ void gemm_phase(PG8_LAS unsigned char* lds, const Gemm g, const Sched& S, const Epi& E, int tid_in) {
;     ...
;         if constexpr (ALIGN_EPI) { if (wr == 0) PG8_BAR; }
;         if constexpr (!Epi::AFTER_DRAIN) { E(acc, cur, wr, wc, fr, fq); S.done(cur); }
;         if (!has_next) break;
; #pragma unroll
;         for (int a = 0; a < 2; ++a)
; #pragma unroll
;             for (int b = 0; b < 2; ++b)
; #pragma unroll
;                 for (int m = 0; m < 4; ++m)
; #pragma unroll
;                     for (int n = 0; n < 2; ++n) acc[a][b][m][n] = (f32x4){0.f, 0.f, 0.f, 0.f};
;         cur = nxt; cA = nA; cB = nB; ++ui;
;         if constexpr (ALIGN_EPI) { if (wr == 1) PG8_BAR; }
;     __device__ __forceinline__ void operator()(const pg8::f32x4 (&acc)[2][2][4][2], const pg8::Unit& u, int wr, int wc, int fr, int fq) const {
;     ...
;             for (int m = 0; m < 4; ++m)
; #pragma unroll
;                 for (int bj = 0; bj < 2; ++bj) {
;                     const u32x4 s = sv[m][bj];
;                     f32x4 v0 = acc[ai][bj][m][0], v1 = acc[ai][bj][m][1];
;                     v0[0] *= bflo(s.x); v0[1] *= bfhi(s.x); v0[2] *= bflo(s.y); v0[3] *= bfhi(s.y); v1[0] *= bflo(s.z); v1[1] *= bfhi(s.z); v1[2] *= bflo(s.w); v1[3] *= bfhi(s.w);
;                     if (ADD) { const u32x4 a = av[m][bj];
;                         v0[0] += bflo(a.x); v0[1] += bfhi(a.x); v0[2] += bflo(a.y); v0[3] += bfhi(a.y); v1[0] += bflo(a.z); v1[1] += bfhi(a.z); v1[2] += bflo(a.w); v1[3] += bfhi(a.w); }
;                     *(u32x4*)(S + off0 + (size_t)m * 16 * 1024 + bj * 128) = pack8(v0, v1);
;                 }
;             asm volatile("" ::: "memory");
;         }
	s_nop 0
	v_lshlrev_b32_e32 v44, 16, v74
	v_and_b32_e32 v45, 0xffff0000, v74
	v_pk_mul_f32 v[44:45], v[48:49], v[44:45]
	v_lshlrev_b32_e32 v48, 16, v76
	v_and_b32_e32 v49, 0xffff0000, v76
	v_lshlrev_b32_e32 v46, 16, v75
	v_and_b32_e32 v47, 0xffff0000, v75
	v_pk_mul_f32 v[48:49], v[40:41], v[48:49]
	v_lshlrev_b32_e32 v40, 16, v77
	v_and_b32_e32 v41, 0xffff0000, v77
	v_pk_mul_f32 v[46:47], v[50:51], v[46:47]
	v_pk_mul_f32 v[50:51], v[42:43], v[40:41]
	v_cvt_pk_bf16_f32 v40, v44, v45
	v_cvt_pk_bf16_f32 v41, v46, v47
	v_cvt_pk_bf16_f32 v42, v48, v49
	v_cvt_pk_bf16_f32 v43, v50, v51
	global_store_dwordx4 v[102:103], v[40:43], off
	s_waitcnt vmcnt(7)
	s_nop 0
	v_lshlrev_b32_e32 v40, 16, v82
	v_and_b32_e32 v41, 0xffff0000, v82
	v_pk_mul_f32 v[36:37], v[36:37], v[40:41]
	v_lshlrev_b32_e32 v40, 16, v83
	v_and_b32_e32 v41, 0xffff0000, v83
	v_pk_mul_f32 v[38:39], v[38:39], v[40:41]
	v_lshlrev_b32_e32 v40, 16, v84
	v_and_b32_e32 v41, 0xffff0000, v84
	v_pk_mul_f32 v[40:41], v[28:29], v[40:41]
	v_lshlrev_b32_e32 v28, 16, v85
	v_and_b32_e32 v29, 0xffff0000, v85
	v_pk_mul_f32 v[42:43], v[30:31], v[28:29]
	v_cvt_pk_bf16_f32 v28, v36, v37
	v_cvt_pk_bf16_f32 v29, v38, v39
	v_cvt_pk_bf16_f32 v30, v40, v41
	v_cvt_pk_bf16_f32 v31, v42, v43
	global_store_dwordx4 v[102:103], v[28:31], off offset:256
	s_waitcnt vmcnt(7)
	s_nop 0
	v_lshlrev_b32_e32 v28, 16, v86
	v_and_b32_e32 v29, 0xffff0000, v86
	v_pk_mul_f32 v[28:29], v[32:33], v[28:29]
	v_lshlrev_b32_e32 v32, 16, v88
	v_and_b32_e32 v33, 0xffff0000, v88
	v_lshlrev_b32_e32 v30, 16, v87
	v_and_b32_e32 v31, 0xffff0000, v87
	v_pk_mul_f32 v[32:33], v[24:25], v[32:33]
	v_lshlrev_b32_e32 v24, 16, v89
	v_and_b32_e32 v25, 0xffff0000, v89
	v_pk_mul_f32 v[30:31], v[34:35], v[30:31]
	v_pk_mul_f32 v[34:35], v[26:27], v[24:25]
	v_cvt_pk_bf16_f32 v24, v28, v29
	v_cvt_pk_bf16_f32 v25, v30, v31
	v_cvt_pk_bf16_f32 v26, v32, v33
	v_cvt_pk_bf16_f32 v27, v34, v35
	global_store_dwordx4 v[104:105], v[24:27], off
	s_waitcnt vmcnt(7)
	s_nop 0
	v_lshlrev_b32_e32 v24, 16, v90
	v_and_b32_e32 v25, 0xffff0000, v90
	v_pk_mul_f32 v[20:21], v[20:21], v[24:25]
	v_lshlrev_b32_e32 v24, 16, v91
	v_and_b32_e32 v25, 0xffff0000, v91
	v_pk_mul_f32 v[22:23], v[22:23], v[24:25]
	v_lshlrev_b32_e32 v24, 16, v92
	v_and_b32_e32 v25, 0xffff0000, v92
	v_pk_mul_f32 v[24:25], v[12:13], v[24:25]
	v_lshlrev_b32_e32 v12, 16, v93
	v_and_b32_e32 v13, 0xffff0000, v93
	v_pk_mul_f32 v[26:27], v[14:15], v[12:13]
	v_cvt_pk_bf16_f32 v12, v20, v21
	v_cvt_pk_bf16_f32 v13, v22, v23
	v_cvt_pk_bf16_f32 v14, v24, v25
	v_cvt_pk_bf16_f32 v15, v26, v27
	global_store_dwordx4 v[104:105], v[12:15], off offset:256
	s_waitcnt vmcnt(7)
	s_nop 0
	v_lshlrev_b32_e32 v12, 16, v94
	v_and_b32_e32 v13, 0xffff0000, v94
	v_pk_mul_f32 v[12:13], v[16:17], v[12:13]
	v_lshlrev_b32_e32 v16, 16, v96
	v_and_b32_e32 v17, 0xffff0000, v96
	v_lshlrev_b32_e32 v14, 16, v95
	v_and_b32_e32 v15, 0xffff0000, v95
	v_pk_mul_f32 v[16:17], v[8:9], v[16:17]
	v_lshlrev_b32_e32 v8, 16, v97
	v_and_b32_e32 v9, 0xffff0000, v97
	v_pk_mul_f32 v[14:15], v[18:19], v[14:15]
	v_pk_mul_f32 v[18:19], v[10:11], v[8:9]
	v_cvt_pk_bf16_f32 v8, v12, v13
	v_cvt_pk_bf16_f32 v9, v14, v15
	v_cvt_pk_bf16_f32 v10, v16, v17
	v_cvt_pk_bf16_f32 v11, v18, v19
	global_store_dwordx4 v[64:65], v[8:11], off
	s_waitcnt vmcnt(7)
	s_nop 0
	v_lshlrev_b32_e32 v8, 16, v98
	v_and_b32_e32 v9, 0xffff0000, v98
	v_pk_mul_f32 v[4:5], v[4:5], v[8:9]
	v_lshlrev_b32_e32 v8, 16, v99
	v_and_b32_e32 v9, 0xffff0000, v99
	v_pk_mul_f32 v[6:7], v[6:7], v[8:9]
	v_lshlrev_b32_e32 v8, 16, v100
	v_and_b32_e32 v9, 0xffff0000, v100
	v_pk_mul_f32 v[8:9], v[0:1], v[8:9]
	v_lshlrev_b32_e32 v0, 16, v101
	v_and_b32_e32 v1, 0xffff0000, v101
	v_pk_mul_f32 v[10:11], v[2:3], v[0:1]
	v_cvt_pk_bf16_f32 v0, v4, v5
	v_cvt_pk_bf16_f32 v1, v6, v7
	v_cvt_pk_bf16_f32 v2, v8, v9
	v_cvt_pk_bf16_f32 v3, v10, v11
	global_store_dwordx4 v[64:65], v[0:3], off offset:256
	s_cbranch_vccnz .LBB0_1297
	s_andn2_b64 vcc, exec, s[4:5]
	s_cbranch_vccnz .LBB0_1296
	s_barrier
	s_branch .LBB0_1296

; __device__ __forceinline__ float bflo(unsigned w) { return __uint_as_float(w << 16); }
; __device__ __forceinline__ float bfhi(unsigned w) { return __uint_as_float(w & 0xffff0000u); }
; __device__ __forceinline__ u32x4 pack8(f32x4 a, f32x4 b) { u32x4 w; w.x = cvtpk(a[0], a[1]); w.y = cvtpk(a[2], a[3]); w.z = cvtpk(b[0], b[1]); w.w = cvtpk(b[2], b[3]); return w; }
;     __device__ __forceinline__ void operator()(const pg8::f32x4 (&acc)[2][2][4][2], const pg8::Unit& u, int wr, int wc, int fr, int fq) const {
;     ...
;             u32x4 sv[4][2], av[4][2];
;             const size_t off0 = (size_t)(u.pm * 256 + ai * 128 + wr * 64 + fr) * 1024 + u.pn * 256 + wc * 32 + 8 * fq;
; #pragma unroll
;             for (int m = 0; m < 4; ++m)
; #pragma unroll
;                 for (int bj = 0; bj < 2; ++bj) { sv[m][bj] = *(const u32x4*)(S + off0 + (size_t)m * 16 * 1024 + bj * 128); if (ADD) av[m][bj] = *(const u32x4*)(A + off0 + (size_t)m * 16 * 1024 + bj * 128); }
; #pragma unroll
;             for (int m = 0; m < 4; ++m)
; #pragma unroll
;                 for (int bj = 0; bj < 2; ++bj) {
;                     const u32x4 s = sv[m][bj];
;                     f32x4 v0 = acc[ai][bj][m][0], v1 = acc[ai][bj][m][1];
;                     v0[0] *= bflo(s.x); v0[1] *= bfhi(s.x); v0[2] *= bflo(s.y); v0[3] *= bfhi(s.y); v1[0] *= bflo(s.z); v1[1] *= bfhi(s.z); v1[2] *= bflo(s.w); v1[3] *= bfhi(s.w);
;                     if (ADD) { const u32x4 a = av[m][bj];
;                         v0[0] += bflo(a.x); v0[1] += bfhi(a.x); v0[2] += bflo(a.y); v0[3] += bfhi(a.y); v1[0] += bflo(a.z); v1[1] += bfhi(a.z); v1[2] += bflo(a.w); v1[3] += bfhi(a.w); }
;                     *(u32x4*)(S + off0 + (size_t)m * 16 * 1024 + bj * 128) = pack8(v0, v1);
;                 }
.LBB0_1343:
	s_lshl_b32 s0, s50, 8
	v_mov_b32_e32 v130, v212
	v_mov_b32_e32 v131, v213
	s_add_i32 s0, s0, s51
	s_mov_b64 s[68:69], s[70:71]
	v_add_u32_e32 v200, s0, v130
	s_lshl_b32 s0, s62, 8
	s_ashr_i32 s1, s0, 31
	v_lshlrev_b32_e32 v130, 3, v131
	v_ashrrev_i32_e32 v131, 31, v130
	s_or_b64 s[0:1], s[0:1], s[70:71]
	v_ashrrev_i32_e32 v201, 31, v200
	v_lshl_add_u64 v[202:203], s[0:1], 0, v[130:131]
	v_lshlrev_b64 v[130:131], 10, v[200:201]
	v_lshl_add_u64 v[130:131], v[202:203], 0, v[130:131]
	v_lshlrev_b64 v[130:131], 1, v[130:131]
	v_lshl_add_u64 v[210:211], s[84:85], 0, v[130:131]
	v_lshl_add_u64 v[130:131], s[80:81], 0, v[130:131]
	global_load_dwordx4 v[234:237], v[210:211], off
	global_load_dwordx4 v[238:241], v[130:131], off
	global_load_dwordx4 v[182:185], v[210:211], off offset:256
	global_load_dwordx4 v[178:181], v[130:131], off offset:256
	v_add_co_u32_e32 v208, vcc, s11, v210
	s_mov_b64 s[0:1], -1
	s_nop 0
	v_addc_co_u32_e32 v209, vcc, 0, v211, vcc
	global_load_dwordx4 v[170:173], v[208:209], off
	v_add_co_u32_e32 v132, vcc, s11, v130
	s_nop 0
	v_addc_co_u32_e32 v133, vcc, 0, v131, vcc
	global_load_dwordx4 v[174:177], v[132:133], off
	global_load_dwordx4 v[166:169], v[208:209], off offset:256
	global_load_dwordx4 v[162:165], v[132:133], off offset:256
	v_add_co_u32_e32 v206, vcc, s33, v210
	s_nop 0
	v_addc_co_u32_e32 v207, vcc, 0, v211, vcc
	global_load_dwordx4 v[154:157], v[206:207], off
	v_add_co_u32_e32 v132, vcc, s33, v130
	s_nop 0
	v_addc_co_u32_e32 v133, vcc, 0, v131, vcc
	global_load_dwordx4 v[158:161], v[132:133], off
	global_load_dwordx4 v[150:153], v[206:207], off offset:256
	global_load_dwordx4 v[146:149], v[132:133], off offset:256
	v_add_co_u32_e32 v204, vcc, s10, v210
	s_nop 0
	v_addc_co_u32_e32 v205, vcc, 0, v211, vcc
	global_load_dwordx4 v[138:141], v[204:205], off
	v_add_co_u32_e32 v130, vcc, s10, v130
	s_nop 0
	v_addc_co_u32_e32 v131, vcc, 0, v131, vcc
	global_load_dwordx4 v[142:145], v[130:131], off
	global_load_dwordx4 v[134:137], v[204:205], off offset:256
	s_nop 0
	global_load_dwordx4 v[130:133], v[130:131], off offset:256
	s_waitcnt vmcnt(11)
	v_lshlrev_b32_e32 v186, 16, v234
	v_and_b32_e32 v187, 0xffff0000, v234
	v_lshlrev_b32_e32 v188, 16, v238
	v_and_b32_e32 v189, 0xffff0000, v238
	v_pk_fma_f32 v[126:127], v[126:127], v[186:187], v[188:189]
	v_lshlrev_b32_e32 v186, 16, v235
	v_and_b32_e32 v187, 0xffff0000, v235
	v_lshlrev_b32_e32 v188, 16, v239
	v_and_b32_e32 v189, 0xffff0000, v239
	v_pk_fma_f32 v[128:129], v[128:129], v[186:187], v[188:189]
	v_lshlrev_b32_e32 v186, 16, v236
	v_and_b32_e32 v187, 0xffff0000, v236
	v_lshlrev_b32_e32 v188, 16, v240
	v_and_b32_e32 v189, 0xffff0000, v240
	v_pk_fma_f32 v[186:187], v[122:123], v[186:187], v[188:189]
	v_lshlrev_b32_e32 v122, 16, v237
	v_and_b32_e32 v123, 0xffff0000, v237
	v_lshlrev_b32_e32 v188, 16, v241
	v_and_b32_e32 v189, 0xffff0000, v241
	v_pk_fma_f32 v[188:189], v[124:125], v[122:123], v[188:189]
	v_cvt_pk_bf16_f32 v122, v126, v127
	v_cvt_pk_bf16_f32 v123, v128, v129
	v_cvt_pk_bf16_f32 v124, v186, v187
	v_cvt_pk_bf16_f32 v125, v188, v189
	global_store_dwordx4 v[210:211], v[122:125], off
	s_nop 1
	v_lshlrev_b32_e32 v122, 16, v182
	v_and_b32_e32 v123, 0xffff0000, v182
	v_lshlrev_b32_e32 v124, 16, v178
	v_and_b32_e32 v125, 0xffff0000, v178
	v_pk_fma_f32 v[118:119], v[118:119], v[122:123], v[124:125]
	v_lshlrev_b32_e32 v122, 16, v183
	v_and_b32_e32 v123, 0xffff0000, v183
	v_lshlrev_b32_e32 v124, 16, v179
	v_and_b32_e32 v125, 0xffff0000, v179
	v_pk_fma_f32 v[120:121], v[120:121], v[122:123], v[124:125]
	v_lshlrev_b32_e32 v122, 16, v184
	v_and_b32_e32 v123, 0xffff0000, v184
	v_lshlrev_b32_e32 v124, 16, v180
	v_and_b32_e32 v125, 0xffff0000, v180
	v_pk_fma_f32 v[122:123], v[114:115], v[122:123], v[124:125]
	v_lshlrev_b32_e32 v114, 16, v185
	v_and_b32_e32 v115, 0xffff0000, v185
	v_lshlrev_b32_e32 v124, 16, v181
	v_and_b32_e32 v125, 0xffff0000, v181
	v_pk_fma_f32 v[124:125], v[116:117], v[114:115], v[124:125]
	v_cvt_pk_bf16_f32 v114, v118, v119
	v_cvt_pk_bf16_f32 v115, v120, v121
	v_cvt_pk_bf16_f32 v116, v122, v123
	v_cvt_pk_bf16_f32 v117, v124, v125
	global_store_dwordx4 v[210:211], v[114:117], off offset:256
	s_nop 1
	v_lshlrev_b32_e32 v114, 16, v170
	v_and_b32_e32 v115, 0xffff0000, v170
	s_waitcnt vmcnt(12)
	v_lshlrev_b32_e32 v116, 16, v174
	v_and_b32_e32 v117, 0xffff0000, v174
	v_pk_fma_f32 v[110:111], v[110:111], v[114:115], v[116:117]
	v_lshlrev_b32_e32 v114, 16, v171
	v_and_b32_e32 v115, 0xffff0000, v171
	v_lshlrev_b32_e32 v116, 16, v175
	v_and_b32_e32 v117, 0xffff0000, v175
	v_pk_fma_f32 v[112:113], v[112:113], v[114:115], v[116:117]
	v_lshlrev_b32_e32 v114, 16, v172
	v_and_b32_e32 v115, 0xffff0000, v172
	v_lshlrev_b32_e32 v116, 16, v176
	v_and_b32_e32 v117, 0xffff0000, v176
	v_pk_fma_f32 v[114:115], v[106:107], v[114:115], v[116:117]
	v_lshlrev_b32_e32 v106, 16, v173
	v_and_b32_e32 v107, 0xffff0000, v173
	v_lshlrev_b32_e32 v116, 16, v177
	v_and_b32_e32 v117, 0xffff0000, v177
	v_pk_fma_f32 v[116:117], v[108:109], v[106:107], v[116:117]
	v_cvt_pk_bf16_f32 v106, v110, v111
	v_cvt_pk_bf16_f32 v107, v112, v113
	v_cvt_pk_bf16_f32 v108, v114, v115
	v_cvt_pk_bf16_f32 v109, v116, v117
	global_store_dwordx4 v[208:209], v[106:109], off
	s_waitcnt vmcnt(12)
	s_nop 0
	v_lshlrev_b32_e32 v106, 16, v166
	v_and_b32_e32 v107, 0xffff0000, v166
	s_waitcnt vmcnt(11)
; __device__ __forceinline__ float bflo(unsigned w) { return __uint_as_float(w << 16); }
; __device__ __forceinline__ float bfhi(unsigned w) { return __uint_as_float(w & 0xffff0000u); }
; __device__ __forceinline__ u32x4 pack8(f32x4 a, f32x4 b) { u32x4 w; w.x = cvtpk(a[0], a[1]); w.y = cvtpk(a[2], a[3]); w.z = cvtpk(b[0], b[1]); w.w = cvtpk(b[2], b[3]); return w; }
;     __device__ __forceinline__ void operator()(const pg8::f32x4 (&acc)[2][2][4][2], const pg8::Unit& u, int wr, int wc, int fr, int fq) const {
;     ...
;             u32x4 sv[4][2], av[4][2];
;             const size_t off0 = (size_t)(u.pm * 256 + ai * 128 + wr * 64 + fr) * 1024 + u.pn * 256 + wc * 32 + 8 * fq;
; #pragma unroll
;             for (int m = 0; m < 4; ++m)
; #pragma unroll
;                 for (int bj = 0; bj < 2; ++bj) { sv[m][bj] = *(const u32x4*)(S + off0 + (size_t)m * 16 * 1024 + bj * 128); if (ADD) av[m][bj] = *(const u32x4*)(A + off0 + (size_t)m * 16 * 1024 + bj * 128); }
; #pragma unroll
;             for (int m = 0; m < 4; ++m)
; #pragma unroll
;                 for (int bj = 0; bj < 2; ++bj) {
;                     const u32x4 s = sv[m][bj];
;                     f32x4 v0 = acc[ai][bj][m][0], v1 = acc[ai][bj][m][1];
;                     v0[0] *= bflo(s.x); v0[1] *= bfhi(s.x); v0[2] *= bflo(s.y); v0[3] *= bfhi(s.y); v1[0] *= bflo(s.z); v1[1] *= bfhi(s.z); v1[2] *= bflo(s.w); v1[3] *= bfhi(s.w);
;                     if (ADD) { const u32x4 a = av[m][bj];
;                         v0[0] += bflo(a.x); v0[1] += bfhi(a.x); v0[2] += bflo(a.y); v0[3] += bfhi(a.y); v1[0] += bflo(a.z); v1[1] += bfhi(a.z); v1[2] += bflo(a.w); v1[3] += bfhi(a.w); }
;                     *(u32x4*)(S + off0 + (size_t)m * 16 * 1024 + bj * 128) = pack8(v0, v1);
;                 }
	v_lshlrev_b32_e32 v108, 16, v162
	v_and_b32_e32 v109, 0xffff0000, v162
	v_pk_fma_f32 v[102:103], v[102:103], v[106:107], v[108:109]
	v_lshlrev_b32_e32 v106, 16, v167
	v_and_b32_e32 v107, 0xffff0000, v167
	v_lshlrev_b32_e32 v108, 16, v163
	v_and_b32_e32 v109, 0xffff0000, v163
	v_pk_fma_f32 v[104:105], v[104:105], v[106:107], v[108:109]
	v_lshlrev_b32_e32 v106, 16, v168
	v_and_b32_e32 v107, 0xffff0000, v168
	v_lshlrev_b32_e32 v108, 16, v164
	v_and_b32_e32 v109, 0xffff0000, v164
	v_pk_fma_f32 v[106:107], v[98:99], v[106:107], v[108:109]
	v_lshlrev_b32_e32 v98, 16, v169
	v_and_b32_e32 v99, 0xffff0000, v169
	v_lshlrev_b32_e32 v108, 16, v165
	v_and_b32_e32 v109, 0xffff0000, v165
	v_pk_fma_f32 v[108:109], v[100:101], v[98:99], v[108:109]
	v_cvt_pk_bf16_f32 v98, v102, v103
	v_cvt_pk_bf16_f32 v99, v104, v105
	v_cvt_pk_bf16_f32 v100, v106, v107
	v_cvt_pk_bf16_f32 v101, v108, v109
	global_store_dwordx4 v[208:209], v[98:101], off offset:256
	s_waitcnt vmcnt(11)
	s_nop 0
	v_lshlrev_b32_e32 v98, 16, v154
	v_and_b32_e32 v99, 0xffff0000, v154
	s_waitcnt vmcnt(10)
	v_lshlrev_b32_e32 v100, 16, v158
	v_and_b32_e32 v101, 0xffff0000, v158
	v_pk_fma_f32 v[94:95], v[94:95], v[98:99], v[100:101]
	v_lshlrev_b32_e32 v98, 16, v155
	v_and_b32_e32 v99, 0xffff0000, v155
	v_lshlrev_b32_e32 v100, 16, v159
	v_and_b32_e32 v101, 0xffff0000, v159
	v_pk_fma_f32 v[96:97], v[96:97], v[98:99], v[100:101]
	v_lshlrev_b32_e32 v98, 16, v156
	v_and_b32_e32 v99, 0xffff0000, v156
	v_lshlrev_b32_e32 v100, 16, v160
	v_and_b32_e32 v101, 0xffff0000, v160
	v_pk_fma_f32 v[98:99], v[90:91], v[98:99], v[100:101]
	v_lshlrev_b32_e32 v90, 16, v157
	v_and_b32_e32 v91, 0xffff0000, v157
	v_lshlrev_b32_e32 v100, 16, v161
	v_and_b32_e32 v101, 0xffff0000, v161
	v_pk_fma_f32 v[100:101], v[92:93], v[90:91], v[100:101]
	v_cvt_pk_bf16_f32 v90, v94, v95
	v_cvt_pk_bf16_f32 v91, v96, v97
	v_cvt_pk_bf16_f32 v92, v98, v99
	v_cvt_pk_bf16_f32 v93, v100, v101
	global_store_dwordx4 v[206:207], v[90:93], off
	s_waitcnt vmcnt(10)
	s_nop 0
	v_lshlrev_b32_e32 v90, 16, v150
	v_and_b32_e32 v91, 0xffff0000, v150
	s_waitcnt vmcnt(9)
	v_lshlrev_b32_e32 v92, 16, v146
	v_and_b32_e32 v93, 0xffff0000, v146
	v_pk_fma_f32 v[86:87], v[86:87], v[90:91], v[92:93]
	v_lshlrev_b32_e32 v90, 16, v151
	v_and_b32_e32 v91, 0xffff0000, v151
	v_lshlrev_b32_e32 v92, 16, v147
	v_and_b32_e32 v93, 0xffff0000, v147
	v_pk_fma_f32 v[88:89], v[88:89], v[90:91], v[92:93]
	v_lshlrev_b32_e32 v90, 16, v152
	v_and_b32_e32 v91, 0xffff0000, v152
	v_lshlrev_b32_e32 v92, 16, v148
	v_and_b32_e32 v93, 0xffff0000, v148
	v_pk_fma_f32 v[90:91], v[82:83], v[90:91], v[92:93]
	v_lshlrev_b32_e32 v82, 16, v153
	v_and_b32_e32 v83, 0xffff0000, v153
	v_lshlrev_b32_e32 v92, 16, v149
	v_and_b32_e32 v93, 0xffff0000, v149
	v_pk_fma_f32 v[92:93], v[84:85], v[82:83], v[92:93]
	v_cvt_pk_bf16_f32 v82, v86, v87
	v_cvt_pk_bf16_f32 v83, v88, v89
	v_cvt_pk_bf16_f32 v84, v90, v91
	v_cvt_pk_bf16_f32 v85, v92, v93
	global_store_dwordx4 v[206:207], v[82:85], off offset:256
	s_waitcnt vmcnt(9)
	s_nop 0
	v_lshlrev_b32_e32 v82, 16, v138
	v_and_b32_e32 v83, 0xffff0000, v138
	s_waitcnt vmcnt(8)
	v_lshlrev_b32_e32 v84, 16, v142
	v_and_b32_e32 v85, 0xffff0000, v142
	v_pk_fma_f32 v[76:77], v[76:77], v[82:83], v[84:85]
	v_lshlrev_b32_e32 v82, 16, v139
	v_and_b32_e32 v83, 0xffff0000, v139
	v_lshlrev_b32_e32 v84, 16, v143
	v_and_b32_e32 v85, 0xffff0000, v143
	v_pk_fma_f32 v[78:79], v[78:79], v[82:83], v[84:85]
	v_lshlrev_b32_e32 v82, 16, v140
	v_and_b32_e32 v83, 0xffff0000, v140
	v_lshlrev_b32_e32 v84, 16, v144
	v_and_b32_e32 v85, 0xffff0000, v144
	v_pk_fma_f32 v[82:83], v[72:73], v[82:83], v[84:85]
	v_lshlrev_b32_e32 v72, 16, v141
	v_and_b32_e32 v73, 0xffff0000, v141
	v_lshlrev_b32_e32 v84, 16, v145
	v_and_b32_e32 v85, 0xffff0000, v145
	v_pk_fma_f32 v[84:85], v[74:75], v[72:73], v[84:85]
	v_cvt_pk_bf16_f32 v72, v76, v77
	v_cvt_pk_bf16_f32 v73, v78, v79
	v_cvt_pk_bf16_f32 v74, v82, v83
	v_cvt_pk_bf16_f32 v75, v84, v85
	global_store_dwordx4 v[204:205], v[72:75], off
	s_waitcnt vmcnt(8)
	s_nop 0
	v_lshlrev_b32_e32 v72, 16, v134
	v_and_b32_e32 v73, 0xffff0000, v134
	s_waitcnt vmcnt(7)
	v_lshlrev_b32_e32 v74, 16, v130
	v_and_b32_e32 v75, 0xffff0000, v130
	v_pk_fma_f32 v[68:69], v[68:69], v[72:73], v[74:75]
	v_lshlrev_b32_e32 v72, 16, v135
	v_and_b32_e32 v73, 0xffff0000, v135
	v_lshlrev_b32_e32 v74, 16, v131
	v_and_b32_e32 v75, 0xffff0000, v131
	v_pk_fma_f32 v[70:71], v[70:71], v[72:73], v[74:75]
	v_lshlrev_b32_e32 v72, 16, v136
	v_and_b32_e32 v73, 0xffff0000, v136
	v_lshlrev_b32_e32 v74, 16, v132
	v_and_b32_e32 v75, 0xffff0000, v132
	v_pk_fma_f32 v[72:73], v[64:65], v[72:73], v[74:75]
	v_lshlrev_b32_e32 v64, 16, v137
	v_and_b32_e32 v65, 0xffff0000, v137
	v_lshlrev_b32_e32 v74, 16, v133
	v_and_b32_e32 v75, 0xffff0000, v133
	v_pk_fma_f32 v[74:75], v[66:67], v[64:65], v[74:75]
	v_cvt_pk_bf16_f32 v64, v68, v69
	v_cvt_pk_bf16_f32 v65, v70, v71
	v_cvt_pk_bf16_f32 v66, v72, v73
	v_cvt_pk_bf16_f32 v67, v74, v75
	global_store_dwordx4 v[204:205], v[64:67], off offset:256
	s_nop 1
	v_add_u32_e32 v64, 0x80, v200
	v_ashrrev_i32_e32 v65, 31, v64
	v_lshlrev_b64 v[64:65], 10, v[64:65]
	v_lshl_add_u64 v[64:65], v[64:65], 0, v[202:203]
	v_lshlrev_b64 v[64:65], 1, v[64:65]
	v_lshl_add_u64 v[136:137], s[84:85], 0, v[64:65]
	v_lshl_add_u64 v[64:65], s[80:81], 0, v[64:65]
	global_load_dwordx4 v[104:107], v[136:137], off
	global_load_dwordx4 v[108:111], v[64:65], off
	global_load_dwordx4 v[112:115], v[136:137], off offset:256
	global_load_dwordx4 v[116:119], v[64:65], off offset:256
	v_add_co_u32_e32 v102, vcc, s11, v136
	s_nop 0
	v_addc_co_u32_e32 v103, vcc, 0, v137, vcc
	global_load_dwordx4 v[120:123], v[102:103], off
	v_add_co_u32_e32 v66, vcc, s11, v64
	s_nop 0
	v_addc_co_u32_e32 v67, vcc, 0, v65, vcc
	global_load_dwordx4 v[124:127], v[66:67], off
	global_load_dwordx4 v[128:131], v[102:103], off offset:256
	global_load_dwordx4 v[132:135], v[66:67], off offset:256
	v_add_co_u32_e32 v100, vcc, s33, v136
	s_nop 0
	v_addc_co_u32_e32 v101, vcc, 0, v137, vcc
	global_load_dwordx4 v[90:93], v[100:101], off
	v_add_co_u32_e32 v66, vcc, s33, v64
	s_nop 0
	v_addc_co_u32_e32 v67, vcc, 0, v65, vcc
	global_load_dwordx4 v[94:97], v[66:67], off
	global_load_dwordx4 v[86:89], v[100:101], off offset:256
	global_load_dwordx4 v[82:85], v[66:67], off offset:256
	v_add_co_u32_e32 v98, vcc, s10, v136
	s_nop 0
	v_addc_co_u32_e32 v99, vcc, 0, v137, vcc
	global_load_dwordx4 v[72:75], v[98:99], off
	v_add_co_u32_e32 v64, vcc, s10, v64
	s_nop 0
	v_addc_co_u32_e32 v65, vcc, 0, v65, vcc
	global_load_dwordx4 v[76:79], v[64:65], off
	global_load_dwordx4 v[68:71], v[98:99], off offset:256
	s_nop 0
	global_load_dwordx4 v[64:67], v[64:65], off offset:256
	s_waitcnt vmcnt(15)
; __device__ __forceinline__ float bflo(unsigned w) { return __uint_as_float(w << 16); }
; __device__ __forceinline__ float bfhi(unsigned w) { return __uint_as_float(w & 0xffff0000u); }
; __device__ __forceinline__ u32x4 pack8(f32x4 a, f32x4 b) { u32x4 w; w.x = cvtpk(a[0], a[1]); w.y = cvtpk(a[2], a[3]); w.z = cvtpk(b[0], b[1]); w.w = cvtpk(b[2], b[3]); return w; }
;     __device__ __forceinline__ void operator()(const pg8::f32x4 (&acc)[2][2][4][2], const pg8::Unit& u, int wr, int wc, int fr, int fq) const {
;     ...
;             for (int m = 0; m < 4; ++m)
; #pragma unroll
;                 for (int bj = 0; bj < 2; ++bj) {
;                     const u32x4 s = sv[m][bj];
;                     f32x4 v0 = acc[ai][bj][m][0], v1 = acc[ai][bj][m][1];
;                     v0[0] *= bflo(s.x); v0[1] *= bfhi(s.x); v0[2] *= bflo(s.y); v0[3] *= bfhi(s.y); v1[0] *= bflo(s.z); v1[1] *= bfhi(s.z); v1[2] *= bflo(s.w); v1[3] *= bfhi(s.w);
;                     if (ADD) { const u32x4 a = av[m][bj];
;                         v0[0] += bflo(a.x); v0[1] += bfhi(a.x); v0[2] += bflo(a.y); v0[3] += bfhi(a.y); v1[0] += bflo(a.z); v1[1] += bfhi(a.z); v1[2] += bflo(a.w); v1[3] += bfhi(a.w); }
;                     *(u32x4*)(S + off0 + (size_t)m * 16 * 1024 + bj * 128) = pack8(v0, v1);
;                 }
	v_lshlrev_b32_e32 v138, 16, v104
	v_and_b32_e32 v139, 0xffff0000, v104
	s_waitcnt vmcnt(14)
	v_lshlrev_b32_e32 v140, 16, v108
	v_and_b32_e32 v141, 0xffff0000, v108
	v_lshlrev_b32_e32 v104, 16, v105
	v_and_b32_e32 v105, 0xffff0000, v105
	v_lshlrev_b32_e32 v108, 16, v109
	v_and_b32_e32 v109, 0xffff0000, v109
	v_pk_fma_f32 v[62:63], v[62:63], v[104:105], v[108:109]
	v_lshlrev_b32_e32 v104, 16, v106
	v_and_b32_e32 v105, 0xffff0000, v106
	v_lshlrev_b32_e32 v108, 16, v110
	v_and_b32_e32 v109, 0xffff0000, v110
	v_pk_fma_f32 v[104:105], v[56:57], v[104:105], v[108:109]
	v_lshlrev_b32_e32 v56, 16, v107
	v_and_b32_e32 v57, 0xffff0000, v107
	v_lshlrev_b32_e32 v106, 16, v111
	v_and_b32_e32 v107, 0xffff0000, v111
	v_pk_fma_f32 v[60:61], v[60:61], v[138:139], v[140:141]
	v_pk_fma_f32 v[106:107], v[58:59], v[56:57], v[106:107]
	v_cvt_pk_bf16_f32 v56, v60, v61
	v_cvt_pk_bf16_f32 v57, v62, v63
	v_cvt_pk_bf16_f32 v58, v104, v105
	v_cvt_pk_bf16_f32 v59, v106, v107
	global_store_dwordx4 v[136:137], v[56:59], off
	s_andn2_b64 vcc, exec, s[38:39]
	s_waitcnt vmcnt(14)
	v_lshlrev_b32_e32 v56, 16, v112
	v_and_b32_e32 v57, 0xffff0000, v112
	s_waitcnt vmcnt(13)
	v_lshlrev_b32_e32 v58, 16, v116
	v_and_b32_e32 v59, 0xffff0000, v116
	v_pk_fma_f32 v[52:53], v[52:53], v[56:57], v[58:59]
	v_lshlrev_b32_e32 v56, 16, v113
	v_and_b32_e32 v57, 0xffff0000, v113
	v_lshlrev_b32_e32 v58, 16, v117
	v_and_b32_e32 v59, 0xffff0000, v117
	v_pk_fma_f32 v[54:55], v[54:55], v[56:57], v[58:59]
	v_lshlrev_b32_e32 v56, 16, v114
	v_and_b32_e32 v57, 0xffff0000, v114
	v_lshlrev_b32_e32 v58, 16, v118
	v_and_b32_e32 v59, 0xffff0000, v118
	v_pk_fma_f32 v[56:57], v[48:49], v[56:57], v[58:59]
	v_lshlrev_b32_e32 v48, 16, v115
	v_and_b32_e32 v49, 0xffff0000, v115
	v_lshlrev_b32_e32 v58, 16, v119
	v_and_b32_e32 v59, 0xffff0000, v119
	v_pk_fma_f32 v[58:59], v[50:51], v[48:49], v[58:59]
	v_cvt_pk_bf16_f32 v48, v52, v53
	v_cvt_pk_bf16_f32 v49, v54, v55
	v_cvt_pk_bf16_f32 v50, v56, v57
	v_cvt_pk_bf16_f32 v51, v58, v59
	global_store_dwordx4 v[136:137], v[48:51], off offset:256
	s_waitcnt vmcnt(13)
	s_nop 0
	v_lshlrev_b32_e32 v48, 16, v120
	v_and_b32_e32 v49, 0xffff0000, v120
	s_waitcnt vmcnt(12)
	v_lshlrev_b32_e32 v50, 16, v124
	v_and_b32_e32 v51, 0xffff0000, v124
	v_pk_fma_f32 v[44:45], v[44:45], v[48:49], v[50:51]
	v_lshlrev_b32_e32 v48, 16, v121
	v_and_b32_e32 v49, 0xffff0000, v121
	v_lshlrev_b32_e32 v50, 16, v125
	v_and_b32_e32 v51, 0xffff0000, v125
	v_pk_fma_f32 v[46:47], v[46:47], v[48:49], v[50:51]
	v_lshlrev_b32_e32 v48, 16, v122
	v_and_b32_e32 v49, 0xffff0000, v122
	v_lshlrev_b32_e32 v50, 16, v126
	v_and_b32_e32 v51, 0xffff0000, v126
	v_pk_fma_f32 v[48:49], v[40:41], v[48:49], v[50:51]
	v_lshlrev_b32_e32 v40, 16, v123
	v_and_b32_e32 v41, 0xffff0000, v123
	v_lshlrev_b32_e32 v50, 16, v127
	v_and_b32_e32 v51, 0xffff0000, v127
	v_pk_fma_f32 v[50:51], v[42:43], v[40:41], v[50:51]
	v_cvt_pk_bf16_f32 v40, v44, v45
	v_cvt_pk_bf16_f32 v41, v46, v47
	v_cvt_pk_bf16_f32 v42, v48, v49
	v_cvt_pk_bf16_f32 v43, v50, v51
	global_store_dwordx4 v[102:103], v[40:43], off
	s_waitcnt vmcnt(12)
	s_nop 0
	v_lshlrev_b32_e32 v40, 16, v128
	v_and_b32_e32 v41, 0xffff0000, v128
	s_waitcnt vmcnt(11)
	v_lshlrev_b32_e32 v42, 16, v132
	v_and_b32_e32 v43, 0xffff0000, v132
	v_pk_fma_f32 v[36:37], v[36:37], v[40:41], v[42:43]
	v_lshlrev_b32_e32 v40, 16, v129
	v_and_b32_e32 v41, 0xffff0000, v129
	v_lshlrev_b32_e32 v42, 16, v133
	v_and_b32_e32 v43, 0xffff0000, v133
	v_pk_fma_f32 v[38:39], v[38:39], v[40:41], v[42:43]
	v_lshlrev_b32_e32 v40, 16, v130
	v_and_b32_e32 v41, 0xffff0000, v130
	v_lshlrev_b32_e32 v42, 16, v134
	v_and_b32_e32 v43, 0xffff0000, v134
	v_pk_fma_f32 v[40:41], v[32:33], v[40:41], v[42:43]
	v_lshlrev_b32_e32 v32, 16, v131
	v_and_b32_e32 v33, 0xffff0000, v131
	v_lshlrev_b32_e32 v42, 16, v135
	v_and_b32_e32 v43, 0xffff0000, v135
	v_pk_fma_f32 v[42:43], v[34:35], v[32:33], v[42:43]
	v_cvt_pk_bf16_f32 v32, v36, v37
	v_cvt_pk_bf16_f32 v33, v38, v39
	v_cvt_pk_bf16_f32 v34, v40, v41
	v_cvt_pk_bf16_f32 v35, v42, v43
	global_store_dwordx4 v[102:103], v[32:35], off offset:256
	s_waitcnt vmcnt(11)
; #define PG8_BAR __builtin_amdgcn_s_barrier()
; __device__ __forceinline__ float bflo(unsigned w) { return __uint_as_float(w << 16); }
; __device__ __forceinline__ float bfhi(unsigned w) { return __uint_as_float(w & 0xffff0000u); }
; __device__ __forceinline__ u32x4 pack8(f32x4 a, f32x4 b) { u32x4 w; w.x = cvtpk(a[0], a[1]); w.y = cvtpk(a[2], a[3]); w.z = cvtpk(b[0], b[1]); w.w = cvtpk(b[2], b[3]); return w; }
; template <class Epi, class Sched, bool ALIGN_EPI = false, bool SP2 = false>
; __device__ __forceinline__ void gemm_phase(PG8_LAS unsigned char* lds, const Gemm g, const Sched& S, const Epi& E, int tid_in) {
;     ...
;         cur = nxt; cA = nA; cB = nB; ++ui;
;         if constexpr (ALIGN_EPI) { if (wr == 1) PG8_BAR; }
;     __device__ __forceinline__ void operator()(const pg8::f32x4 (&acc)[2][2][4][2], const pg8::Unit& u, int wr, int wc, int fr, int fq) const {
;     ...
;             for (int m = 0; m < 4; ++m)
; #pragma unroll
;                 for (int bj = 0; bj < 2; ++bj) {
;                     const u32x4 s = sv[m][bj];
;                     f32x4 v0 = acc[ai][bj][m][0], v1 = acc[ai][bj][m][1];
;                     v0[0] *= bflo(s.x); v0[1] *= bfhi(s.x); v0[2] *= bflo(s.y); v0[3] *= bfhi(s.y); v1[0] *= bflo(s.z); v1[1] *= bfhi(s.z); v1[2] *= bflo(s.w); v1[3] *= bfhi(s.w);
;                     if (ADD) { const u32x4 a = av[m][bj];
;                         v0[0] += bflo(a.x); v0[1] += bfhi(a.x); v0[2] += bflo(a.y); v0[3] += bfhi(a.y); v1[0] += bflo(a.z); v1[1] += bfhi(a.z); v1[2] += bflo(a.w); v1[3] += bfhi(a.w); }
;                     *(u32x4*)(S + off0 + (size_t)m * 16 * 1024 + bj * 128) = pack8(v0, v1);
;                 }
	s_nop 0
	v_lshlrev_b32_e32 v32, 16, v90
	v_and_b32_e32 v33, 0xffff0000, v90
	s_waitcnt vmcnt(10)
	v_lshlrev_b32_e32 v34, 16, v94
	v_and_b32_e32 v35, 0xffff0000, v94
	v_pk_fma_f32 v[28:29], v[28:29], v[32:33], v[34:35]
	v_lshlrev_b32_e32 v32, 16, v91
	v_and_b32_e32 v33, 0xffff0000, v91
	v_lshlrev_b32_e32 v34, 16, v95
	v_and_b32_e32 v35, 0xffff0000, v95
	v_pk_fma_f32 v[30:31], v[30:31], v[32:33], v[34:35]
	v_lshlrev_b32_e32 v32, 16, v92
	v_and_b32_e32 v33, 0xffff0000, v92
	v_lshlrev_b32_e32 v34, 16, v96
	v_and_b32_e32 v35, 0xffff0000, v96
	v_pk_fma_f32 v[32:33], v[24:25], v[32:33], v[34:35]
	v_lshlrev_b32_e32 v24, 16, v93
	v_and_b32_e32 v25, 0xffff0000, v93
	v_lshlrev_b32_e32 v34, 16, v97
	v_and_b32_e32 v35, 0xffff0000, v97
	v_pk_fma_f32 v[34:35], v[26:27], v[24:25], v[34:35]
	v_cvt_pk_bf16_f32 v24, v28, v29
	v_cvt_pk_bf16_f32 v25, v30, v31
	v_cvt_pk_bf16_f32 v26, v32, v33
	v_cvt_pk_bf16_f32 v27, v34, v35
	global_store_dwordx4 v[100:101], v[24:27], off
	s_waitcnt vmcnt(10)
	s_nop 0
	v_lshlrev_b32_e32 v24, 16, v86
	v_and_b32_e32 v25, 0xffff0000, v86
	s_waitcnt vmcnt(9)
	v_lshlrev_b32_e32 v26, 16, v82
	v_and_b32_e32 v27, 0xffff0000, v82
	v_pk_fma_f32 v[20:21], v[20:21], v[24:25], v[26:27]
	v_lshlrev_b32_e32 v24, 16, v87
	v_and_b32_e32 v25, 0xffff0000, v87
	v_lshlrev_b32_e32 v26, 16, v83
	v_and_b32_e32 v27, 0xffff0000, v83
	v_pk_fma_f32 v[22:23], v[22:23], v[24:25], v[26:27]
	v_lshlrev_b32_e32 v24, 16, v88
	v_and_b32_e32 v25, 0xffff0000, v88
	v_lshlrev_b32_e32 v26, 16, v84
	v_and_b32_e32 v27, 0xffff0000, v84
	v_pk_fma_f32 v[24:25], v[16:17], v[24:25], v[26:27]
	v_lshlrev_b32_e32 v16, 16, v89
	v_and_b32_e32 v17, 0xffff0000, v89
	v_lshlrev_b32_e32 v26, 16, v85
	v_and_b32_e32 v27, 0xffff0000, v85
	v_pk_fma_f32 v[26:27], v[18:19], v[16:17], v[26:27]
	v_cvt_pk_bf16_f32 v16, v20, v21
	v_cvt_pk_bf16_f32 v17, v22, v23
	v_cvt_pk_bf16_f32 v18, v24, v25
	v_cvt_pk_bf16_f32 v19, v26, v27
	global_store_dwordx4 v[100:101], v[16:19], off offset:256
	s_waitcnt vmcnt(9)
	s_nop 0
	v_lshlrev_b32_e32 v16, 16, v72
	v_and_b32_e32 v17, 0xffff0000, v72
	s_waitcnt vmcnt(8)
	v_lshlrev_b32_e32 v18, 16, v76
	v_and_b32_e32 v19, 0xffff0000, v76
	v_pk_fma_f32 v[12:13], v[12:13], v[16:17], v[18:19]
	v_lshlrev_b32_e32 v16, 16, v73
	v_and_b32_e32 v17, 0xffff0000, v73
	v_lshlrev_b32_e32 v18, 16, v77
	v_and_b32_e32 v19, 0xffff0000, v77
	v_pk_fma_f32 v[14:15], v[14:15], v[16:17], v[18:19]
	v_lshlrev_b32_e32 v16, 16, v74
	v_and_b32_e32 v17, 0xffff0000, v74
	v_lshlrev_b32_e32 v18, 16, v78
	v_and_b32_e32 v19, 0xffff0000, v78
	v_pk_fma_f32 v[16:17], v[8:9], v[16:17], v[18:19]
	v_lshlrev_b32_e32 v8, 16, v75
	v_and_b32_e32 v9, 0xffff0000, v75
	v_lshlrev_b32_e32 v18, 16, v79
	v_and_b32_e32 v19, 0xffff0000, v79
	v_pk_fma_f32 v[18:19], v[10:11], v[8:9], v[18:19]
	v_cvt_pk_bf16_f32 v8, v12, v13
	v_cvt_pk_bf16_f32 v9, v14, v15
	v_cvt_pk_bf16_f32 v10, v16, v17
	v_cvt_pk_bf16_f32 v11, v18, v19
	global_store_dwordx4 v[98:99], v[8:11], off
	s_waitcnt vmcnt(8)
	s_nop 0
	v_lshlrev_b32_e32 v8, 16, v68
	v_and_b32_e32 v9, 0xffff0000, v68
	s_waitcnt vmcnt(7)
	v_lshlrev_b32_e32 v10, 16, v64
	v_and_b32_e32 v11, 0xffff0000, v64
	v_pk_fma_f32 v[4:5], v[4:5], v[8:9], v[10:11]
	v_lshlrev_b32_e32 v8, 16, v69
	v_and_b32_e32 v9, 0xffff0000, v69
	v_lshlrev_b32_e32 v10, 16, v65
	v_and_b32_e32 v11, 0xffff0000, v65
	v_pk_fma_f32 v[6:7], v[6:7], v[8:9], v[10:11]
	v_lshlrev_b32_e32 v8, 16, v70
	v_and_b32_e32 v9, 0xffff0000, v70
	v_lshlrev_b32_e32 v10, 16, v66
	v_and_b32_e32 v11, 0xffff0000, v66
	v_pk_fma_f32 v[8:9], v[0:1], v[8:9], v[10:11]
	v_lshlrev_b32_e32 v0, 16, v71
	v_and_b32_e32 v1, 0xffff0000, v71
	v_lshlrev_b32_e32 v10, 16, v67
	v_and_b32_e32 v11, 0xffff0000, v67
	v_pk_fma_f32 v[10:11], v[2:3], v[0:1], v[10:11]
	v_cvt_pk_bf16_f32 v0, v4, v5
	v_cvt_pk_bf16_f32 v1, v6, v7
	v_cvt_pk_bf16_f32 v2, v8, v9
	v_cvt_pk_bf16_f32 v3, v10, v11
	global_store_dwordx4 v[98:99], v[0:3], off offset:256
	s_cbranch_vccnz .LBB0_1332
	s_andn2_b64 vcc, exec, s[4:5]
	s_cbranch_vccnz .LBB0_1331
	s_barrier
	s_branch .LBB0_1331
